# attention: 3-slot LDS ring (K/V tile loads issued two tiles ahead, counted vmcnt(6)), last tile loaded into the slot the item epilogue expects
# baseline (speedup 1.0000x reference)
.LBB0_1480:
	v_readfirstlane_b32 s44, v203
	v_readfirstlane_b32 s45, v205
	s_mov_b64 s[40:41], s[94:95]
	s_mov_b64 s[42:43], s[94:95]
	s_movk_i32 s46, 0x2b
	s_add_u32 s45, s45, 0x2000
	v_add_u32_e32 v191, 0xc000, v173
	v_add_u32_e32 v193, 0xc000, v171
	v_add_u32_e32 v195, 0xc000, v169
	v_add_u32_e32 v197, 0xc000, v167
	s_add_u32 m0, s44, 0xc000
	s_nop 0
	global_load_lds_dwordx4 v200, s[40:41]
	s_add_u32 m0, s44, 0xc400
	s_nop 0
	global_load_lds_dwordx4 v190, s[40:41]
	s_add_u32 m0, s45, 0xc000
	s_nop 0
	global_load_lds_dwordx4 v192, s[42:43]
	s_add_u32 m0, s45, 0xc400
	s_nop 0
	global_load_lds_dwordx4 v194, s[42:43]
	s_add_u32 m0, s45, 0xc800
	s_nop 0
	global_load_lds_dwordx4 v196, s[42:43]
	s_add_u32 m0, s45, 0xcc00
	s_nop 0
	global_load_lds_dwordx4 v198, s[42:43]
	s_add_u32 s40, s40, 0x18000
	s_addc_u32 s41, s41, 0
	s_add_u32 s42, s42, 0x80
	s_addc_u32 s43, s43, 0
.Latt_loop:
	s_waitcnt vmcnt(6)
	s_barrier
	ds_read_b128 v[64:67], v173 offset:24576
	ds_read_b128 v[68:71], v173 offset:28672
	s_mov_b32 m0, s44
	ds_read_b128 v[72:75], v171 offset:24576
	global_load_lds_dwordx4 v200, s[40:41]
	s_add_u32 m0, s44, 0x400
	ds_read_b128 v[76:79], v171 offset:28672
	global_load_lds_dwordx4 v190, s[40:41]
	s_mov_b32 m0, s45
	ds_read_b128 v[216:219], v169 offset:24576
	global_load_lds_dwordx4 v192, s[42:43]
	s_add_u32 m0, s45, 0x400
	ds_read_b128 v[220:223], v169 offset:28672
	global_load_lds_dwordx4 v194, s[42:43]
	s_add_u32 m0, s45, 0x800
	ds_read_b128 v[224:227], v167 offset:24576
	global_load_lds_dwordx4 v196, s[42:43]
	s_add_u32 m0, s45, 0xc00
	ds_read_b128 v[228:231], v167 offset:28672
	global_load_lds_dwordx4 v198, s[42:43]
	s_add_u32 s40, s40, 0x18000
	s_addc_u32 s41, s41, 0
	s_add_u32 s42, s42, 0x80
	s_addc_u32 s43, s43, 0
	ds_read_b128 v[232:235], v173 offset:32768
	ds_read_b128 v[236:239], v173 offset:36864
	ds_read_b128 v[240:243], v173 offset:40960
	ds_read_b128 v[244:247], v173 offset:45056
	s_waitcnt lgkmcnt(11)
	v_mfma_f32_32x32x16_bf16 v[112:127], v[64:67], v[140:143], v[96:111]
	ds_read_b128 v[64:67], v171 offset:32768
	s_waitcnt lgkmcnt(11)
	v_mfma_f32_32x32x16_bf16 v[80:95], v[68:71], v[140:143], v[96:111]
	ds_read_b128 v[68:71], v171 offset:36864
	s_waitcnt lgkmcnt(11)
	v_mfma_f32_32x32x16_bf16 v[112:127], v[72:75], v[136:139], v[112:127]
	ds_read_b128 v[72:75], v171 offset:40960
	s_waitcnt lgkmcnt(11)
	v_mfma_f32_32x32x16_bf16 v[80:95], v[76:79], v[136:139], v[80:95]
	ds_read_b128 v[76:79], v171 offset:45056
	s_waitcnt lgkmcnt(11)
	v_mfma_f32_32x32x16_bf16 v[112:127], v[216:219], v[132:135], v[112:127]
	ds_read_b128 v[216:219], v169 offset:32768
	s_waitcnt lgkmcnt(11)
	v_mfma_f32_32x32x16_bf16 v[80:95], v[220:223], v[132:135], v[80:95]
	ds_read_b128 v[220:223], v169 offset:36864
	s_waitcnt lgkmcnt(11)
	v_mfma_f32_32x32x16_bf16 v[112:127], v[224:227], v[128:131], v[112:127]
	ds_read_b128 v[224:227], v169 offset:40960
	s_waitcnt lgkmcnt(11)
	v_mfma_f32_32x32x16_bf16 v[80:95], v[228:231], v[128:131], v[80:95]
	ds_read_b128 v[228:231], v169 offset:45056
	s_nop 7
	s_nop 3
	v_max3_f32 v175, v112, v113, v114
	v_max3_f32 v177, v115, v116, v117
	v_max3_f32 v179, v118, v119, v120
	v_max3_f32 v181, v121, v122, v123
	v_max3_f32 v248, v124, v125, v126
	v_max3_f32 v249, v127, v80, v81
	v_max3_f32 v250, v82, v83, v84
	v_max3_f32 v251, v85, v86, v87
	v_max3_f32 v253, v88, v89, v90
	v_max3_f32 v254, v91, v92, v93
	v_max_f32_e32 v255, v94, v95
	v_max3_f32 v175, v175, v177, v179
	v_max3_f32 v181, v181, v248, v249
	v_max3_f32 v250, v250, v251, v253
	v_max_f32_e32 v254, v254, v255
	v_max3_f32 v175, v175, v181, v250
	v_max_f32_e32 v175, v175, v254
	v_mov_b32_e32 v177, v175
	s_nop 1
	v_permlane32_swap_b32_e32 v175, v177
	v_max_f32_e32 v175, v175, v177
	v_cmp_lt_f32_e32 vcc, 0, v175
	s_cbranch_vccnz .Latt_resc_a
.Latt_cont_a:
	v_exp_f32_e32 v112, v112
	v_exp_f32_e32 v113, v113
	v_exp_f32_e32 v114, v114
	v_exp_f32_e32 v115, v115
	v_exp_f32_e32 v116, v116
	v_exp_f32_e32 v117, v117
	v_exp_f32_e32 v118, v118
	v_exp_f32_e32 v119, v119
	v_add_f32_e32 v183, v112, v113
	v_add_f32_e32 v183, v183, v114
	v_add_f32_e32 v183, v183, v115
	v_add_f32_e32 v183, v183, v116
	v_add_f32_e32 v183, v183, v117
	v_add_f32_e32 v183, v183, v118
	v_add_f32_e32 v183, v183, v119
	v_cvt_pk_bf16_f32 v112, v112, v113
	v_cvt_pk_bf16_f32 v113, v114, v115
	v_cvt_pk_bf16_f32 v114, v116, v117
	v_cvt_pk_bf16_f32 v115, v118, v119
	v_exp_f32_e32 v120, v120
	v_exp_f32_e32 v121, v121
	s_waitcnt lgkmcnt(8)
	v_mfma_f32_32x32x16_bf16 v[48:63], v[232:235], v[112:115], v[48:63]
	v_exp_f32_e32 v122, v122
	v_exp_f32_e32 v123, v123
	v_exp_f32_e32 v124, v124
	v_mfma_f32_32x32x16_bf16 v[32:47], v[236:239], v[112:115], v[32:47]
	v_exp_f32_e32 v125, v125
	v_exp_f32_e32 v126, v126
	v_exp_f32_e32 v127, v127
	v_mfma_f32_32x32x16_bf16 v[16:31], v[240:243], v[112:115], v[16:31]
	v_add_f32_e32 v185, v120, v121
	v_add_f32_e32 v185, v185, v122
	v_add_f32_e32 v185, v185, v123
	v_add_f32_e32 v185, v185, v124
	v_add_f32_e32 v185, v185, v125
	v_add_f32_e32 v185, v185, v126
	v_mfma_f32_32x32x16_bf16 v[0:15], v[244:247], v[112:115], v[0:15]
	ds_read_b128 v[232:235], v167 offset:32768
	ds_read_b128 v[236:239], v167 offset:36864
	ds_read_b128 v[240:243], v167 offset:40960
	ds_read_b128 v[244:247], v167 offset:45056
	v_add_f32_e32 v185, v185, v127
	v_cvt_pk_bf16_f32 v116, v120, v121
	v_cvt_pk_bf16_f32 v117, v122, v123
	v_cvt_pk_bf16_f32 v118, v124, v125
	v_cvt_pk_bf16_f32 v119, v126, v127
	s_nop 0
	s_waitcnt lgkmcnt(8)
	v_mfma_f32_32x32x16_bf16 v[48:63], v[64:67], v[116:119], v[48:63]
	v_exp_f32_e32 v80, v80
	v_exp_f32_e32 v81, v81
	v_exp_f32_e32 v82, v82
	v_mfma_f32_32x32x16_bf16 v[32:47], v[68:71], v[116:119], v[32:47]
	v_exp_f32_e32 v83, v83
	v_exp_f32_e32 v84, v84
	v_exp_f32_e32 v85, v85
	v_mfma_f32_32x32x16_bf16 v[16:31], v[72:75], v[116:119], v[16:31]
	v_exp_f32_e32 v86, v86
	v_exp_f32_e32 v87, v87
	v_add_f32_e32 v187, v80, v81
	v_add_f32_e32 v187, v187, v82
	v_mfma_f32_32x32x16_bf16 v[0:15], v[76:79], v[116:119], v[0:15]
	v_add_f32_e32 v187, v187, v83
	v_add_f32_e32 v187, v187, v84
	v_add_f32_e32 v187, v187, v85
	v_add_f32_e32 v187, v187, v86
	v_add_f32_e32 v187, v187, v87
	v_cvt_pk_bf16_f32 v80, v80, v81
	v_cvt_pk_bf16_f32 v81, v82, v83
	v_cvt_pk_bf16_f32 v82, v84, v85
	v_cvt_pk_bf16_f32 v83, v86, v87
	s_nop 0
	s_waitcnt lgkmcnt(4)
	v_mfma_f32_32x32x16_bf16 v[48:63], v[216:219], v[80:83], v[48:63]
	v_exp_f32_e32 v88, v88
	v_exp_f32_e32 v89, v89
	v_exp_f32_e32 v90, v90
	v_mfma_f32_32x32x16_bf16 v[32:47], v[220:223], v[80:83], v[32:47]
	v_exp_f32_e32 v91, v91
	v_exp_f32_e32 v92, v92
	v_exp_f32_e32 v93, v93
	v_mfma_f32_32x32x16_bf16 v[16:31], v[224:227], v[80:83], v[16:31]
	v_exp_f32_e32 v94, v94
	v_exp_f32_e32 v95, v95
	v_add_f32_e32 v215, v88, v89
	v_add_f32_e32 v215, v215, v90
	v_mfma_f32_32x32x16_bf16 v[0:15], v[228:231], v[80:83], v[0:15]
	v_add_f32_e32 v215, v215, v91
	v_add_f32_e32 v215, v215, v92
	v_add_f32_e32 v215, v215, v93
	v_add_f32_e32 v215, v215, v94
	v_add_f32_e32 v215, v215, v95
	v_cvt_pk_bf16_f32 v84, v88, v89
	v_cvt_pk_bf16_f32 v85, v90, v91
	v_cvt_pk_bf16_f32 v86, v92, v93
	v_cvt_pk_bf16_f32 v87, v94, v95
	s_nop 0
	s_waitcnt lgkmcnt(0)
	v_mfma_f32_32x32x16_bf16 v[48:63], v[232:235], v[84:87], v[48:63]
	v_add_f32_e32 v183, v183, v185
	v_add_f32_e32 v187, v187, v215
	v_add_f32_e32 v183, v183, v187
	v_mov_b32_e32 v185, v183
	v_mfma_f32_32x32x16_bf16 v[32:47], v[236:239], v[84:87], v[32:47]
	v_mfma_f32_32x32x16_bf16 v[16:31], v[240:243], v[84:87], v[16:31]
	v_mfma_f32_32x32x16_bf16 v[0:15], v[244:247], v[84:87], v[0:15]
	s_nop 0
	s_nop 0
	v_permlane32_swap_b32_e32 v183, v185
	v_add_f32_e32 v183, v183, v185
	v_add_f32_e32 v189, v189, v183
	s_waitcnt vmcnt(6)
	s_barrier
	ds_read_b128 v[64:67], v191 offset:0
	ds_read_b128 v[68:71], v191 offset:4096
	s_add_u32 m0, s44, 0x6000
	ds_read_b128 v[72:75], v193 offset:0
	global_load_lds_dwordx4 v200, s[40:41]
	s_add_u32 m0, s44, 0x6400
	ds_read_b128 v[76:79], v193 offset:4096
	global_load_lds_dwordx4 v190, s[40:41]
	s_add_u32 m0, s45, 0x6000
	ds_read_b128 v[216:219], v195 offset:0
	global_load_lds_dwordx4 v192, s[42:43]
	s_add_u32 m0, s45, 0x6400
	ds_read_b128 v[220:223], v195 offset:4096
	global_load_lds_dwordx4 v194, s[42:43]
	s_add_u32 m0, s45, 0x6800
	ds_read_b128 v[224:227], v197 offset:0
	global_load_lds_dwordx4 v196, s[42:43]
	s_add_u32 m0, s45, 0x6c00
	ds_read_b128 v[228:231], v197 offset:4096
	global_load_lds_dwordx4 v198, s[42:43]
	s_add_u32 s40, s40, 0x18000
	s_addc_u32 s41, s41, 0
	s_add_u32 s42, s42, 0x80
	s_addc_u32 s43, s43, 0
	ds_read_b128 v[232:235], v191 offset:8192
	ds_read_b128 v[236:239], v191 offset:12288
	ds_read_b128 v[240:243], v191 offset:16384
	ds_read_b128 v[244:247], v191 offset:20480
	s_waitcnt lgkmcnt(11)
	v_mfma_f32_32x32x16_bf16 v[112:127], v[64:67], v[140:143], v[96:111]
	ds_read_b128 v[64:67], v193 offset:8192
	s_waitcnt lgkmcnt(11)
	v_mfma_f32_32x32x16_bf16 v[80:95], v[68:71], v[140:143], v[96:111]
	ds_read_b128 v[68:71], v193 offset:12288
	s_waitcnt lgkmcnt(11)
	v_mfma_f32_32x32x16_bf16 v[112:127], v[72:75], v[136:139], v[112:127]
	ds_read_b128 v[72:75], v193 offset:16384
	s_waitcnt lgkmcnt(11)
	v_mfma_f32_32x32x16_bf16 v[80:95], v[76:79], v[136:139], v[80:95]
	ds_read_b128 v[76:79], v193 offset:20480
	s_waitcnt lgkmcnt(11)
	v_mfma_f32_32x32x16_bf16 v[112:127], v[216:219], v[132:135], v[112:127]
	ds_read_b128 v[216:219], v195 offset:8192
	s_waitcnt lgkmcnt(11)
	v_mfma_f32_32x32x16_bf16 v[80:95], v[220:223], v[132:135], v[80:95]
	ds_read_b128 v[220:223], v195 offset:12288
	s_waitcnt lgkmcnt(11)
	v_mfma_f32_32x32x16_bf16 v[112:127], v[224:227], v[128:131], v[112:127]
	ds_read_b128 v[224:227], v195 offset:16384
	s_waitcnt lgkmcnt(11)
	v_mfma_f32_32x32x16_bf16 v[80:95], v[228:231], v[128:131], v[80:95]
	ds_read_b128 v[228:231], v195 offset:20480
	s_nop 7
	s_nop 3
	v_max3_f32 v175, v112, v113, v114
	v_max3_f32 v177, v115, v116, v117
	v_max3_f32 v179, v118, v119, v120
	v_max3_f32 v181, v121, v122, v123
	v_max3_f32 v248, v124, v125, v126
	v_max3_f32 v249, v127, v80, v81
	v_max3_f32 v250, v82, v83, v84
	v_max3_f32 v251, v85, v86, v87
	v_max3_f32 v253, v88, v89, v90
	v_max3_f32 v254, v91, v92, v93
	v_max_f32_e32 v255, v94, v95
	v_max3_f32 v175, v175, v177, v179
	v_max3_f32 v181, v181, v248, v249
	v_max3_f32 v250, v250, v251, v253
	v_max_f32_e32 v254, v254, v255
	v_max3_f32 v175, v175, v181, v250
	v_max_f32_e32 v175, v175, v254
	v_mov_b32_e32 v177, v175
	s_nop 1
	v_permlane32_swap_b32_e32 v175, v177
	v_max_f32_e32 v175, v175, v177
	v_cmp_lt_f32_e32 vcc, 0, v175
	s_cbranch_vccnz .Latt_resc_b
.Latt_cont_b:
	v_exp_f32_e32 v112, v112
	v_exp_f32_e32 v113, v113
	v_exp_f32_e32 v114, v114
	v_exp_f32_e32 v115, v115
	v_exp_f32_e32 v116, v116
	v_exp_f32_e32 v117, v117
	v_exp_f32_e32 v118, v118
	v_exp_f32_e32 v119, v119
	v_add_f32_e32 v183, v112, v113
	v_add_f32_e32 v183, v183, v114
	v_add_f32_e32 v183, v183, v115
	v_add_f32_e32 v183, v183, v116
	v_add_f32_e32 v183, v183, v117
	v_add_f32_e32 v183, v183, v118
	v_add_f32_e32 v183, v183, v119
	v_cvt_pk_bf16_f32 v112, v112, v113
	v_cvt_pk_bf16_f32 v113, v114, v115
	v_cvt_pk_bf16_f32 v114, v116, v117
	v_cvt_pk_bf16_f32 v115, v118, v119
	v_exp_f32_e32 v120, v120
	v_exp_f32_e32 v121, v121
	s_waitcnt lgkmcnt(8)
	v_mfma_f32_32x32x16_bf16 v[48:63], v[232:235], v[112:115], v[48:63]
	v_exp_f32_e32 v122, v122
	v_exp_f32_e32 v123, v123
	v_exp_f32_e32 v124, v124
	v_mfma_f32_32x32x16_bf16 v[32:47], v[236:239], v[112:115], v[32:47]
	v_exp_f32_e32 v125, v125
	v_exp_f32_e32 v126, v126
	v_exp_f32_e32 v127, v127
	v_mfma_f32_32x32x16_bf16 v[16:31], v[240:243], v[112:115], v[16:31]
	v_add_f32_e32 v185, v120, v121
	v_add_f32_e32 v185, v185, v122
	v_add_f32_e32 v185, v185, v123
	v_add_f32_e32 v185, v185, v124
	v_add_f32_e32 v185, v185, v125
	v_add_f32_e32 v185, v185, v126
	v_mfma_f32_32x32x16_bf16 v[0:15], v[244:247], v[112:115], v[0:15]
	ds_read_b128 v[232:235], v197 offset:8192
	ds_read_b128 v[236:239], v197 offset:12288
	ds_read_b128 v[240:243], v197 offset:16384
	ds_read_b128 v[244:247], v197 offset:20480
	v_add_f32_e32 v185, v185, v127
	v_cvt_pk_bf16_f32 v116, v120, v121
	v_cvt_pk_bf16_f32 v117, v122, v123
	v_cvt_pk_bf16_f32 v118, v124, v125
	v_cvt_pk_bf16_f32 v119, v126, v127
	s_nop 0
	s_waitcnt lgkmcnt(8)
	v_mfma_f32_32x32x16_bf16 v[48:63], v[64:67], v[116:119], v[48:63]
	v_exp_f32_e32 v80, v80
	v_exp_f32_e32 v81, v81
	v_exp_f32_e32 v82, v82
	v_mfma_f32_32x32x16_bf16 v[32:47], v[68:71], v[116:119], v[32:47]
	v_exp_f32_e32 v83, v83
	v_exp_f32_e32 v84, v84
	v_exp_f32_e32 v85, v85
	v_mfma_f32_32x32x16_bf16 v[16:31], v[72:75], v[116:119], v[16:31]
	v_exp_f32_e32 v86, v86
	v_exp_f32_e32 v87, v87
	v_add_f32_e32 v187, v80, v81
	v_add_f32_e32 v187, v187, v82
	v_mfma_f32_32x32x16_bf16 v[0:15], v[76:79], v[116:119], v[0:15]
	v_add_f32_e32 v187, v187, v83
	v_add_f32_e32 v187, v187, v84
	v_add_f32_e32 v187, v187, v85
	v_add_f32_e32 v187, v187, v86
	v_add_f32_e32 v187, v187, v87
	v_cvt_pk_bf16_f32 v80, v80, v81
	v_cvt_pk_bf16_f32 v81, v82, v83
	v_cvt_pk_bf16_f32 v82, v84, v85
	v_cvt_pk_bf16_f32 v83, v86, v87
	s_nop 0
	s_waitcnt lgkmcnt(4)
	v_mfma_f32_32x32x16_bf16 v[48:63], v[216:219], v[80:83], v[48:63]
	v_exp_f32_e32 v88, v88
	v_exp_f32_e32 v89, v89
	v_exp_f32_e32 v90, v90
	v_mfma_f32_32x32x16_bf16 v[32:47], v[220:223], v[80:83], v[32:47]
	v_exp_f32_e32 v91, v91
	v_exp_f32_e32 v92, v92
	v_exp_f32_e32 v93, v93
	v_mfma_f32_32x32x16_bf16 v[16:31], v[224:227], v[80:83], v[16:31]
	v_exp_f32_e32 v94, v94
	v_exp_f32_e32 v95, v95
	v_add_f32_e32 v215, v88, v89
	v_add_f32_e32 v215, v215, v90
	v_mfma_f32_32x32x16_bf16 v[0:15], v[228:231], v[80:83], v[0:15]
	v_add_f32_e32 v215, v215, v91
	v_add_f32_e32 v215, v215, v92
	v_add_f32_e32 v215, v215, v93
	v_add_f32_e32 v215, v215, v94
	v_add_f32_e32 v215, v215, v95
	v_cvt_pk_bf16_f32 v84, v88, v89
	v_cvt_pk_bf16_f32 v85, v90, v91
	v_cvt_pk_bf16_f32 v86, v92, v93
	v_cvt_pk_bf16_f32 v87, v94, v95
	s_nop 0
	s_waitcnt lgkmcnt(0)
	v_mfma_f32_32x32x16_bf16 v[48:63], v[232:235], v[84:87], v[48:63]
	v_add_f32_e32 v183, v183, v185
	v_add_f32_e32 v187, v187, v215
	v_add_f32_e32 v183, v183, v187
	v_mov_b32_e32 v185, v183
	v_mfma_f32_32x32x16_bf16 v[32:47], v[236:239], v[84:87], v[32:47]
	v_mfma_f32_32x32x16_bf16 v[16:31], v[240:243], v[84:87], v[16:31]
	v_mfma_f32_32x32x16_bf16 v[0:15], v[244:247], v[84:87], v[0:15]
	s_nop 0
	s_nop 0
	v_permlane32_swap_b32_e32 v183, v185
	v_add_f32_e32 v183, v183, v185
	v_add_f32_e32 v189, v189, v183
	s_waitcnt vmcnt(6)
	s_barrier
	ds_read_b128 v[64:67], v173 offset:0
	ds_read_b128 v[68:71], v173 offset:4096
	ds_read_b128 v[72:75], v171 offset:0
	ds_read_b128 v[76:79], v171 offset:4096
	ds_read_b128 v[216:219], v169 offset:0
	ds_read_b128 v[220:223], v169 offset:4096
	ds_read_b128 v[224:227], v167 offset:0
	ds_read_b128 v[228:231], v167 offset:4096
	s_cmp_eq_u32 s46, 1
	s_cbranch_scc1 .Latt_noissue_c
	s_add_u32 m0, s44, 0xc000
	s_nop 0
	global_load_lds_dwordx4 v200, s[40:41]
	s_add_u32 m0, s44, 0xc400
	s_nop 0
	global_load_lds_dwordx4 v190, s[40:41]
	s_add_u32 m0, s45, 0xc000
	s_nop 0
	global_load_lds_dwordx4 v192, s[42:43]
	s_add_u32 m0, s45, 0xc400
	s_nop 0
	global_load_lds_dwordx4 v194, s[42:43]
	s_add_u32 m0, s45, 0xc800
	s_nop 0
	global_load_lds_dwordx4 v196, s[42:43]
	s_add_u32 m0, s45, 0xcc00
	s_nop 0
	global_load_lds_dwordx4 v198, s[42:43]
	s_add_u32 s40, s40, 0x18000
	s_addc_u32 s41, s41, 0
	s_add_u32 s42, s42, 0x80
	s_addc_u32 s43, s43, 0
.Latt_noissue_c:
	ds_read_b128 v[232:235], v173 offset:8192
	ds_read_b128 v[236:239], v173 offset:12288
	ds_read_b128 v[240:243], v173 offset:16384
	ds_read_b128 v[244:247], v173 offset:20480
	s_waitcnt lgkmcnt(11)
	v_mfma_f32_32x32x16_bf16 v[112:127], v[64:67], v[140:143], v[96:111]
	ds_read_b128 v[64:67], v171 offset:8192
	s_waitcnt lgkmcnt(11)
	v_mfma_f32_32x32x16_bf16 v[80:95], v[68:71], v[140:143], v[96:111]
	ds_read_b128 v[68:71], v171 offset:12288
	s_waitcnt lgkmcnt(11)
	v_mfma_f32_32x32x16_bf16 v[112:127], v[72:75], v[136:139], v[112:127]
	ds_read_b128 v[72:75], v171 offset:16384
	s_waitcnt lgkmcnt(11)
	v_mfma_f32_32x32x16_bf16 v[80:95], v[76:79], v[136:139], v[80:95]
	ds_read_b128 v[76:79], v171 offset:20480
	s_waitcnt lgkmcnt(11)
	v_mfma_f32_32x32x16_bf16 v[112:127], v[216:219], v[132:135], v[112:127]
	ds_read_b128 v[216:219], v169 offset:8192
	s_waitcnt lgkmcnt(11)
	v_mfma_f32_32x32x16_bf16 v[80:95], v[220:223], v[132:135], v[80:95]
	ds_read_b128 v[220:223], v169 offset:12288
	s_waitcnt lgkmcnt(11)
	v_mfma_f32_32x32x16_bf16 v[112:127], v[224:227], v[128:131], v[112:127]
	ds_read_b128 v[224:227], v169 offset:16384
	s_waitcnt lgkmcnt(11)
	v_mfma_f32_32x32x16_bf16 v[80:95], v[228:231], v[128:131], v[80:95]
	ds_read_b128 v[228:231], v169 offset:20480
	s_nop 7
	s_nop 3
	v_max3_f32 v175, v112, v113, v114
	v_max3_f32 v177, v115, v116, v117
	v_max3_f32 v179, v118, v119, v120
	v_max3_f32 v181, v121, v122, v123
	v_max3_f32 v248, v124, v125, v126
	v_max3_f32 v249, v127, v80, v81
	v_max3_f32 v250, v82, v83, v84
	v_max3_f32 v251, v85, v86, v87
	v_max3_f32 v253, v88, v89, v90
	v_max3_f32 v254, v91, v92, v93
	v_max_f32_e32 v255, v94, v95
	v_max3_f32 v175, v175, v177, v179
	v_max3_f32 v181, v181, v248, v249
	v_max3_f32 v250, v250, v251, v253
	v_max_f32_e32 v254, v254, v255
	v_max3_f32 v175, v175, v181, v250
	v_max_f32_e32 v175, v175, v254
	v_mov_b32_e32 v177, v175
	s_nop 1
	v_permlane32_swap_b32_e32 v175, v177
	v_max_f32_e32 v175, v175, v177
	v_cmp_lt_f32_e32 vcc, 0, v175
	s_cbranch_vccnz .Latt_resc_c
.Latt_cont_c:
	v_exp_f32_e32 v112, v112
	v_exp_f32_e32 v113, v113
	v_exp_f32_e32 v114, v114
	v_exp_f32_e32 v115, v115
	v_exp_f32_e32 v116, v116
	v_exp_f32_e32 v117, v117
	v_exp_f32_e32 v118, v118
	v_exp_f32_e32 v119, v119
	v_add_f32_e32 v183, v112, v113
	v_add_f32_e32 v183, v183, v114
	v_add_f32_e32 v183, v183, v115
	v_add_f32_e32 v183, v183, v116
	v_add_f32_e32 v183, v183, v117
	v_add_f32_e32 v183, v183, v118
	v_add_f32_e32 v183, v183, v119
	v_cvt_pk_bf16_f32 v112, v112, v113
	v_cvt_pk_bf16_f32 v113, v114, v115
	v_cvt_pk_bf16_f32 v114, v116, v117
	v_cvt_pk_bf16_f32 v115, v118, v119
	v_exp_f32_e32 v120, v120
	v_exp_f32_e32 v121, v121
	s_waitcnt lgkmcnt(8)
	v_mfma_f32_32x32x16_bf16 v[48:63], v[232:235], v[112:115], v[48:63]
	v_exp_f32_e32 v122, v122
	v_exp_f32_e32 v123, v123
	v_exp_f32_e32 v124, v124
	v_mfma_f32_32x32x16_bf16 v[32:47], v[236:239], v[112:115], v[32:47]
	v_exp_f32_e32 v125, v125
	v_exp_f32_e32 v126, v126
	v_exp_f32_e32 v127, v127
	v_mfma_f32_32x32x16_bf16 v[16:31], v[240:243], v[112:115], v[16:31]
	v_add_f32_e32 v185, v120, v121
	v_add_f32_e32 v185, v185, v122
	v_add_f32_e32 v185, v185, v123
	v_add_f32_e32 v185, v185, v124
	v_add_f32_e32 v185, v185, v125
	v_add_f32_e32 v185, v185, v126
	v_mfma_f32_32x32x16_bf16 v[0:15], v[244:247], v[112:115], v[0:15]
	ds_read_b128 v[232:235], v167 offset:8192
	ds_read_b128 v[236:239], v167 offset:12288
	ds_read_b128 v[240:243], v167 offset:16384
	ds_read_b128 v[244:247], v167 offset:20480
	v_add_f32_e32 v185, v185, v127
	v_cvt_pk_bf16_f32 v116, v120, v121
	v_cvt_pk_bf16_f32 v117, v122, v123
	v_cvt_pk_bf16_f32 v118, v124, v125
	v_cvt_pk_bf16_f32 v119, v126, v127
	s_nop 0
	s_waitcnt lgkmcnt(8)
	v_mfma_f32_32x32x16_bf16 v[48:63], v[64:67], v[116:119], v[48:63]
	v_exp_f32_e32 v80, v80
	v_exp_f32_e32 v81, v81
	v_exp_f32_e32 v82, v82
	v_mfma_f32_32x32x16_bf16 v[32:47], v[68:71], v[116:119], v[32:47]
	v_exp_f32_e32 v83, v83
	v_exp_f32_e32 v84, v84
	v_exp_f32_e32 v85, v85
	v_mfma_f32_32x32x16_bf16 v[16:31], v[72:75], v[116:119], v[16:31]
	v_exp_f32_e32 v86, v86
	v_exp_f32_e32 v87, v87
	v_add_f32_e32 v187, v80, v81
	v_add_f32_e32 v187, v187, v82
	v_mfma_f32_32x32x16_bf16 v[0:15], v[76:79], v[116:119], v[0:15]
	v_add_f32_e32 v187, v187, v83
	v_add_f32_e32 v187, v187, v84
	v_add_f32_e32 v187, v187, v85
	v_add_f32_e32 v187, v187, v86
	v_add_f32_e32 v187, v187, v87
	v_cvt_pk_bf16_f32 v80, v80, v81
	v_cvt_pk_bf16_f32 v81, v82, v83
	v_cvt_pk_bf16_f32 v82, v84, v85
	v_cvt_pk_bf16_f32 v83, v86, v87
	s_nop 0
	s_waitcnt lgkmcnt(4)
	v_mfma_f32_32x32x16_bf16 v[48:63], v[216:219], v[80:83], v[48:63]
	v_exp_f32_e32 v88, v88
	v_exp_f32_e32 v89, v89
	v_exp_f32_e32 v90, v90
	v_mfma_f32_32x32x16_bf16 v[32:47], v[220:223], v[80:83], v[32:47]
	v_exp_f32_e32 v91, v91
	v_exp_f32_e32 v92, v92
	v_exp_f32_e32 v93, v93
	v_mfma_f32_32x32x16_bf16 v[16:31], v[224:227], v[80:83], v[16:31]
	v_exp_f32_e32 v94, v94
	v_exp_f32_e32 v95, v95
	v_add_f32_e32 v215, v88, v89
	v_add_f32_e32 v215, v215, v90
	v_mfma_f32_32x32x16_bf16 v[0:15], v[228:231], v[80:83], v[0:15]
	v_add_f32_e32 v215, v215, v91
	v_add_f32_e32 v215, v215, v92
	v_add_f32_e32 v215, v215, v93
	v_add_f32_e32 v215, v215, v94
	v_add_f32_e32 v215, v215, v95
	v_cvt_pk_bf16_f32 v84, v88, v89
	v_cvt_pk_bf16_f32 v85, v90, v91
	v_cvt_pk_bf16_f32 v86, v92, v93
	v_cvt_pk_bf16_f32 v87, v94, v95
	s_nop 0
	s_waitcnt lgkmcnt(0)
	v_mfma_f32_32x32x16_bf16 v[48:63], v[232:235], v[84:87], v[48:63]
	v_add_f32_e32 v183, v183, v185
	v_add_f32_e32 v187, v187, v215
	v_add_f32_e32 v183, v183, v187
	v_mov_b32_e32 v185, v183
	v_mfma_f32_32x32x16_bf16 v[32:47], v[236:239], v[84:87], v[32:47]
	v_mfma_f32_32x32x16_bf16 v[16:31], v[240:243], v[84:87], v[16:31]
	v_mfma_f32_32x32x16_bf16 v[0:15], v[244:247], v[84:87], v[0:15]
	s_nop 0
	s_nop 0
	v_permlane32_swap_b32_e32 v183, v185
	v_add_f32_e32 v183, v183, v185
	v_add_f32_e32 v189, v189, v183
	s_sub_u32 s46, s46, 1
	s_cmp_lg_u32 s46, 0
	s_cbranch_scc1 .Latt_loop
	s_waitcnt vmcnt(0)
	s_barrier
	ds_read_b128 v[64:67], v173 offset:24576
	ds_read_b128 v[68:71], v173 offset:28672
	ds_read_b128 v[72:75], v171 offset:24576
	ds_read_b128 v[76:79], v171 offset:28672
	ds_read_b128 v[216:219], v169 offset:24576
	ds_read_b128 v[220:223], v169 offset:28672
	ds_read_b128 v[224:227], v167 offset:24576
	ds_read_b128 v[228:231], v167 offset:28672
	ds_read_b128 v[232:235], v173 offset:32768
	ds_read_b128 v[236:239], v173 offset:36864
	ds_read_b128 v[240:243], v173 offset:40960
	ds_read_b128 v[244:247], v173 offset:45056
	s_waitcnt lgkmcnt(11)
	v_mfma_f32_32x32x16_bf16 v[112:127], v[64:67], v[140:143], v[96:111]
	ds_read_b128 v[64:67], v171 offset:32768
	s_waitcnt lgkmcnt(11)
	v_mfma_f32_32x32x16_bf16 v[80:95], v[68:71], v[140:143], v[96:111]
	ds_read_b128 v[68:71], v171 offset:36864
	s_waitcnt lgkmcnt(11)
	v_mfma_f32_32x32x16_bf16 v[112:127], v[72:75], v[136:139], v[112:127]
	ds_read_b128 v[72:75], v171 offset:40960
	s_waitcnt lgkmcnt(11)
	v_mfma_f32_32x32x16_bf16 v[80:95], v[76:79], v[136:139], v[80:95]
	ds_read_b128 v[76:79], v171 offset:45056
	s_waitcnt lgkmcnt(11)
	v_mfma_f32_32x32x16_bf16 v[112:127], v[216:219], v[132:135], v[112:127]
	ds_read_b128 v[216:219], v169 offset:32768
	s_waitcnt lgkmcnt(11)
	v_mfma_f32_32x32x16_bf16 v[80:95], v[220:223], v[132:135], v[80:95]
	ds_read_b128 v[220:223], v169 offset:36864
	s_waitcnt lgkmcnt(11)
	v_mfma_f32_32x32x16_bf16 v[112:127], v[224:227], v[128:131], v[112:127]
	ds_read_b128 v[224:227], v169 offset:40960
	s_waitcnt lgkmcnt(11)
	v_mfma_f32_32x32x16_bf16 v[80:95], v[228:231], v[128:131], v[80:95]
	ds_read_b128 v[228:231], v169 offset:45056
	s_nop 7
	s_nop 3
	v_max3_f32 v175, v112, v113, v114
	v_max3_f32 v177, v115, v116, v117
	v_max3_f32 v179, v118, v119, v120
	v_max3_f32 v181, v121, v122, v123
	v_max3_f32 v248, v124, v125, v126
	v_max3_f32 v249, v127, v80, v81
	v_max3_f32 v250, v82, v83, v84
	v_max3_f32 v251, v85, v86, v87
	v_max3_f32 v253, v88, v89, v90
	v_max3_f32 v254, v91, v92, v93
	v_max_f32_e32 v255, v94, v95
	v_max3_f32 v175, v175, v177, v179
	v_max3_f32 v181, v181, v248, v249
	v_max3_f32 v250, v250, v251, v253
	v_max_f32_e32 v254, v254, v255
	v_max3_f32 v175, v175, v181, v250
	v_max_f32_e32 v175, v175, v254
	v_mov_b32_e32 v177, v175
	s_nop 1
	v_permlane32_swap_b32_e32 v175, v177
	v_max_f32_e32 v175, v175, v177
	v_cmp_lt_f32_e32 vcc, 0, v175
	s_cbranch_vccnz .Latt_resc_t
.Latt_cont_t:
	v_exp_f32_e32 v112, v112
	v_exp_f32_e32 v113, v113
	v_exp_f32_e32 v114, v114
	v_exp_f32_e32 v115, v115
	v_exp_f32_e32 v116, v116
	v_exp_f32_e32 v117, v117
	v_exp_f32_e32 v118, v118
	v_exp_f32_e32 v119, v119
	v_add_f32_e32 v183, v112, v113
	v_add_f32_e32 v183, v183, v114
	v_add_f32_e32 v183, v183, v115
	v_add_f32_e32 v183, v183, v116
	v_add_f32_e32 v183, v183, v117
	v_add_f32_e32 v183, v183, v118
	v_add_f32_e32 v183, v183, v119
	v_cvt_pk_bf16_f32 v112, v112, v113
	v_cvt_pk_bf16_f32 v113, v114, v115
	v_cvt_pk_bf16_f32 v114, v116, v117
	v_cvt_pk_bf16_f32 v115, v118, v119
	v_exp_f32_e32 v120, v120
	v_exp_f32_e32 v121, v121
	s_waitcnt lgkmcnt(8)
	v_mfma_f32_32x32x16_bf16 v[48:63], v[232:235], v[112:115], v[48:63]
	v_exp_f32_e32 v122, v122
	v_exp_f32_e32 v123, v123
	v_exp_f32_e32 v124, v124
	v_mfma_f32_32x32x16_bf16 v[32:47], v[236:239], v[112:115], v[32:47]
	v_exp_f32_e32 v125, v125
	v_exp_f32_e32 v126, v126
	v_exp_f32_e32 v127, v127
	v_mfma_f32_32x32x16_bf16 v[16:31], v[240:243], v[112:115], v[16:31]
	v_add_f32_e32 v185, v120, v121
	v_add_f32_e32 v185, v185, v122
	v_add_f32_e32 v185, v185, v123
	v_add_f32_e32 v185, v185, v124
	v_add_f32_e32 v185, v185, v125
	v_add_f32_e32 v185, v185, v126
	v_mfma_f32_32x32x16_bf16 v[0:15], v[244:247], v[112:115], v[0:15]
	ds_read_b128 v[232:235], v167 offset:32768
	ds_read_b128 v[236:239], v167 offset:36864
	ds_read_b128 v[240:243], v167 offset:40960
	ds_read_b128 v[244:247], v167 offset:45056
	v_add_f32_e32 v185, v185, v127
	v_cvt_pk_bf16_f32 v116, v120, v121
	v_cvt_pk_bf16_f32 v117, v122, v123
	v_cvt_pk_bf16_f32 v118, v124, v125
	v_cvt_pk_bf16_f32 v119, v126, v127
	s_nop 0
	s_waitcnt lgkmcnt(8)
	v_mfma_f32_32x32x16_bf16 v[48:63], v[64:67], v[116:119], v[48:63]
	v_exp_f32_e32 v80, v80
	v_exp_f32_e32 v81, v81
	v_exp_f32_e32 v82, v82
	v_mfma_f32_32x32x16_bf16 v[32:47], v[68:71], v[116:119], v[32:47]
	v_exp_f32_e32 v83, v83
	v_exp_f32_e32 v84, v84
	v_exp_f32_e32 v85, v85
	v_mfma_f32_32x32x16_bf16 v[16:31], v[72:75], v[116:119], v[16:31]
	v_exp_f32_e32 v86, v86
	v_exp_f32_e32 v87, v87
	v_add_f32_e32 v187, v80, v81
	v_add_f32_e32 v187, v187, v82
	v_mfma_f32_32x32x16_bf16 v[0:15], v[76:79], v[116:119], v[0:15]
	v_add_f32_e32 v187, v187, v83
	v_add_f32_e32 v187, v187, v84
	v_add_f32_e32 v187, v187, v85
	v_add_f32_e32 v187, v187, v86
	v_add_f32_e32 v187, v187, v87
	v_cvt_pk_bf16_f32 v80, v80, v81
	v_cvt_pk_bf16_f32 v81, v82, v83
	v_cvt_pk_bf16_f32 v82, v84, v85
	v_cvt_pk_bf16_f32 v83, v86, v87
	s_nop 0
	s_waitcnt lgkmcnt(4)
	v_mfma_f32_32x32x16_bf16 v[48:63], v[216:219], v[80:83], v[48:63]
	v_exp_f32_e32 v88, v88
	v_exp_f32_e32 v89, v89
	v_exp_f32_e32 v90, v90
	v_mfma_f32_32x32x16_bf16 v[32:47], v[220:223], v[80:83], v[32:47]
	v_exp_f32_e32 v91, v91
	v_exp_f32_e32 v92, v92
	v_exp_f32_e32 v93, v93
	v_mfma_f32_32x32x16_bf16 v[16:31], v[224:227], v[80:83], v[16:31]
	v_exp_f32_e32 v94, v94
	v_exp_f32_e32 v95, v95
	v_add_f32_e32 v215, v88, v89
	v_add_f32_e32 v215, v215, v90
	v_mfma_f32_32x32x16_bf16 v[0:15], v[228:231], v[80:83], v[0:15]
	v_add_f32_e32 v215, v215, v91
	v_add_f32_e32 v215, v215, v92
	v_add_f32_e32 v215, v215, v93
	v_add_f32_e32 v215, v215, v94
	v_add_f32_e32 v215, v215, v95
	v_cvt_pk_bf16_f32 v84, v88, v89
	v_cvt_pk_bf16_f32 v85, v90, v91
	v_cvt_pk_bf16_f32 v86, v92, v93
	v_cvt_pk_bf16_f32 v87, v94, v95
	s_nop 0
	s_waitcnt lgkmcnt(0)
	v_mfma_f32_32x32x16_bf16 v[48:63], v[232:235], v[84:87], v[48:63]
	v_add_f32_e32 v183, v183, v185
	v_add_f32_e32 v187, v187, v215
	v_add_f32_e32 v183, v183, v187
	v_mov_b32_e32 v185, v183
	v_mfma_f32_32x32x16_bf16 v[32:47], v[236:239], v[84:87], v[32:47]
	v_mfma_f32_32x32x16_bf16 v[16:31], v[240:243], v[84:87], v[16:31]
	v_mfma_f32_32x32x16_bf16 v[0:15], v[244:247], v[84:87], v[0:15]
	s_nop 0
	s_nop 0
	v_permlane32_swap_b32_e32 v183, v185
	v_add_f32_e32 v183, v183, v185
	v_add_f32_e32 v189, v189, v183
	s_barrier
	s_add_u32 m0, s44, 0x6000
	s_nop 0
	global_load_lds_dwordx4 v200, s[40:41]
	s_add_u32 m0, s44, 0x6400
	s_nop 0
	global_load_lds_dwordx4 v190, s[40:41]
	s_add_u32 m0, s45, 0x6000
	s_nop 0
	global_load_lds_dwordx4 v192, s[42:43]
	s_add_u32 m0, s45, 0x6400
	s_nop 0
	global_load_lds_dwordx4 v194, s[42:43]
	s_add_u32 m0, s45, 0x6800
	s_nop 0
	global_load_lds_dwordx4 v196, s[42:43]
	s_add_u32 m0, s45, 0x6c00
	s_nop 0
	global_load_lds_dwordx4 v198, s[42:43]
	v_mov_b64_e32 v[64:65], v[96:97]
	v_mov_b64_e32 v[66:67], v[98:99]
	v_mov_b64_e32 v[68:69], v[100:101]
	v_mov_b64_e32 v[70:71], v[102:103]
	v_mov_b64_e32 v[72:73], v[104:105]
	v_mov_b64_e32 v[74:75], v[106:107]
	v_mov_b64_e32 v[76:77], v[108:109]
	v_mov_b64_e32 v[78:79], v[110:111]
	s_branch .LBB0_1482
